# phase 15: K/V staging (once per kv group) with all 16 row loads in flight before the LDS writes; other heads branch around the staging block
# speedup vs baseline: 1.0099x; 1.0099x over previous
.LBB0_765:
	s_and_b32 s99, s53, 7
	s_cmp_eq_u32 s99, 0
	s_cselect_b64 s[100:101], -1, 0
	s_bfe_u32 s6, s53, 0x70004
	s_lshl_b32 s8, s6, 7
	v_mov_b32_e32 v85, v205
	s_add_i32 s10, s8, 0xffffff80
	v_and_b32_e32 v10, 7, v85
	v_ashrrev_i32_e32 v1, 3, v85
	s_lshl_b32 s4, s53, 3
	v_lshlrev_b32_e32 v2, 3, v10
	v_add_u32_e32 v11, s10, v1
	s_and_b32 s7, s38, 0xffffc000
	s_and_b32 s9, s4, 64
	v_cmp_lt_i32_e32 vcc, -1, v11
	v_mov_b32_e32 v0, 0
	v_lshlrev_b32_e32 v80, 1, v2
	v_mov_b32_e32 v6, 0
	v_mov_b32_e32 v7, 0
	v_mov_b32_e32 v8, 0
	v_mov_b32_e32 v9, 0
	v_mov_b32_e32 v2, 0
	v_mov_b32_e32 v3, 0
	v_mov_b32_e32 v4, 0
	v_mov_b32_e32 v5, 0
	s_barrier
	s_mov_b64 vcc, s[100:101]
	s_cbranch_vccnz .Lp15_stage
	s_mov_b64 s[4:5], exec
	s_branch .LBB0_764
.Lp15_stage:
	v_lshlrev_b32_e32 v12, 4, v10
	v_mad_u32_u24 v13, v10, s41, v12
	s_lshl_b32 s16, s9, 1
	v_mov_b64_e32 v[136:137], s[44:45]
	v_lshl_add_u64 v[136:137], v[136:137], 0, s[16:17]
	v_lshl_add_u64 v[136:137], v[136:137], 0, v[80:81]
	v_mov_b32_e32 v138, v1
	v_mov_b32_e32 v146, 0
	v_mov_b32_e32 v147, 0
	v_mov_b32_e32 v148, 0
	v_mov_b32_e32 v149, 0
	v_mov_b32_e32 v150, 0
	v_mov_b32_e32 v151, 0
	v_mov_b32_e32 v152, 0
	v_mov_b32_e32 v153, 0
	v_add_u32_e32 v204, s10, v138
	v_cmp_lt_i32_e32 vcc, -1, v204
	v_add_u32_e32 v206, s7, v204
	s_and_saveexec_b64 s[4:5], vcc
	v_mad_i64_i32 v[202:203], s[12:13], v206, s40, v[136:137]
	global_load_dwordx4 v[146:149], v[202:203], off offset:2048
	global_load_dwordx4 v[150:153], v[202:203], off offset:2304
	s_or_b64 exec, exec, s[4:5]
	v_add_u32_e32 v139, 32, v1
	v_mov_b32_e32 v154, 0
	v_mov_b32_e32 v155, 0
	v_mov_b32_e32 v156, 0
	v_mov_b32_e32 v157, 0
	v_mov_b32_e32 v158, 0
	v_mov_b32_e32 v159, 0
	v_mov_b32_e32 v160, 0
	v_mov_b32_e32 v161, 0
	v_add_u32_e32 v204, s10, v139
	v_cmp_lt_i32_e32 vcc, -1, v204
	v_add_u32_e32 v206, s7, v204
	s_and_saveexec_b64 s[4:5], vcc
	v_mad_i64_i32 v[202:203], s[12:13], v206, s40, v[136:137]
	global_load_dwordx4 v[154:157], v[202:203], off offset:2048
	global_load_dwordx4 v[158:161], v[202:203], off offset:2304
	s_or_b64 exec, exec, s[4:5]
	v_add_u32_e32 v140, 64, v1
	v_mov_b32_e32 v162, 0
	v_mov_b32_e32 v163, 0
	v_mov_b32_e32 v164, 0
	v_mov_b32_e32 v165, 0
	v_mov_b32_e32 v166, 0
	v_mov_b32_e32 v167, 0
	v_mov_b32_e32 v168, 0
	v_mov_b32_e32 v169, 0
	v_add_u32_e32 v204, s10, v140
	v_cmp_lt_i32_e32 vcc, -1, v204
	v_add_u32_e32 v206, s7, v204
	s_and_saveexec_b64 s[4:5], vcc
	v_mad_i64_i32 v[202:203], s[12:13], v206, s40, v[136:137]
	global_load_dwordx4 v[162:165], v[202:203], off offset:2048
	global_load_dwordx4 v[166:169], v[202:203], off offset:2304
	s_or_b64 exec, exec, s[4:5]
	v_add_u32_e32 v141, 96, v1
	v_mov_b32_e32 v170, 0
	v_mov_b32_e32 v171, 0
	v_mov_b32_e32 v172, 0
	v_mov_b32_e32 v173, 0
	v_mov_b32_e32 v174, 0
	v_mov_b32_e32 v175, 0
	v_mov_b32_e32 v176, 0
	v_mov_b32_e32 v177, 0
	v_add_u32_e32 v204, s10, v141
	v_cmp_lt_i32_e32 vcc, -1, v204
	v_add_u32_e32 v206, s7, v204
	s_and_saveexec_b64 s[4:5], vcc
	v_mad_i64_i32 v[202:203], s[12:13], v206, s40, v[136:137]
	global_load_dwordx4 v[170:173], v[202:203], off offset:2048
	global_load_dwordx4 v[174:177], v[202:203], off offset:2304
	s_or_b64 exec, exec, s[4:5]
	v_add_u32_e32 v142, 128, v1
	v_mov_b32_e32 v178, 0
	v_mov_b32_e32 v179, 0
	v_mov_b32_e32 v180, 0
	v_mov_b32_e32 v181, 0
	v_mov_b32_e32 v182, 0
	v_mov_b32_e32 v183, 0
	v_mov_b32_e32 v184, 0
	v_mov_b32_e32 v185, 0
	v_add_u32_e32 v204, s10, v142
	v_cmp_lt_i32_e32 vcc, -1, v204
	v_add_u32_e32 v206, s7, v204
	s_and_saveexec_b64 s[4:5], vcc
	v_mad_i64_i32 v[202:203], s[12:13], v206, s40, v[136:137]
	global_load_dwordx4 v[178:181], v[202:203], off offset:2048
	global_load_dwordx4 v[182:185], v[202:203], off offset:2304
	s_or_b64 exec, exec, s[4:5]
	v_add_u32_e32 v143, 160, v1
	v_mov_b32_e32 v186, 0
	v_mov_b32_e32 v187, 0
	v_mov_b32_e32 v188, 0
	v_mov_b32_e32 v189, 0
	v_mov_b32_e32 v190, 0
	v_mov_b32_e32 v191, 0
	v_mov_b32_e32 v192, 0
	v_mov_b32_e32 v193, 0
	v_add_u32_e32 v204, s10, v143
	v_cmp_lt_i32_e32 vcc, -1, v204
	v_add_u32_e32 v206, s7, v204
	s_and_saveexec_b64 s[4:5], vcc
	v_mad_i64_i32 v[202:203], s[12:13], v206, s40, v[136:137]
	global_load_dwordx4 v[186:189], v[202:203], off offset:2048
	global_load_dwordx4 v[190:193], v[202:203], off offset:2304
	s_or_b64 exec, exec, s[4:5]
	v_add_u32_e32 v144, 192, v1
	v_mov_b32_e32 v194, 0
	v_mov_b32_e32 v195, 0
	v_mov_b32_e32 v196, 0
	v_mov_b32_e32 v197, 0
	v_mov_b32_e32 v198, 0
	v_mov_b32_e32 v199, 0
	v_mov_b32_e32 v200, 0
	v_mov_b32_e32 v201, 0
	v_add_u32_e32 v204, s10, v144
	v_cmp_lt_i32_e32 vcc, -1, v204
	v_add_u32_e32 v206, s7, v204
	s_and_saveexec_b64 s[4:5], vcc
	v_mad_i64_i32 v[202:203], s[12:13], v206, s40, v[136:137]
	global_load_dwordx4 v[194:197], v[202:203], off offset:2048
	global_load_dwordx4 v[198:201], v[202:203], off offset:2304
	s_or_b64 exec, exec, s[4:5]
	v_add_u32_e32 v8, 224, v1
	v_mov_b32_e32 v4, 0
	v_mov_b32_e32 v5, 0
	v_mov_b32_e32 v6, 0
	v_mov_b32_e32 v7, 0
	v_mov_b32_e32 v0, 0
	v_mov_b32_e32 v1, 0
	v_mov_b32_e32 v2, 0
	v_mov_b32_e32 v3, 0
	v_add_u32_e32 v204, s10, v8
	v_cmp_lt_i32_e32 vcc, -1, v204
	v_add_u32_e32 v206, s7, v204
	s_and_saveexec_b64 s[4:5], vcc
	v_mad_i64_i32 v[202:203], s[12:13], v206, s40, v[136:137]
	global_load_dwordx4 v[4:7], v[202:203], off offset:2048
	global_load_dwordx4 v[0:3], v[202:203], off offset:2304
	s_or_b64 exec, exec, s[4:5]
	v_mad_u32_u24 v10, v138, s50, v12
	v_lshl_add_u32 v208, v138, 1, v13
	s_waitcnt vmcnt(15)
	ds_write_b128 v10, v[146:149]
	s_waitcnt vmcnt(14)
	ds_write_b16 v208, v150 offset:36864
	ds_write_b16_d16_hi v208, v150 offset:37392
	ds_write_b16 v208, v151 offset:37920
	ds_write_b16_d16_hi v208, v151 offset:38448
	ds_write_b16 v208, v152 offset:38976
	ds_write_b16_d16_hi v208, v152 offset:39504
	ds_write_b16 v208, v153 offset:40032
	ds_write_b16_d16_hi v208, v153 offset:40560
	v_mad_u32_u24 v10, v139, s50, v12
	v_lshl_add_u32 v208, v139, 1, v13
	s_waitcnt vmcnt(13)
	ds_write_b128 v10, v[154:157]
	s_waitcnt vmcnt(12)
	ds_write_b16 v208, v158 offset:36864
	ds_write_b16_d16_hi v208, v158 offset:37392
	ds_write_b16 v208, v159 offset:37920
	ds_write_b16_d16_hi v208, v159 offset:38448
	ds_write_b16 v208, v160 offset:38976
	ds_write_b16_d16_hi v208, v160 offset:39504
	ds_write_b16 v208, v161 offset:40032
	ds_write_b16_d16_hi v208, v161 offset:40560
	v_mad_u32_u24 v10, v140, s50, v12
	v_lshl_add_u32 v208, v140, 1, v13
	s_waitcnt vmcnt(11)
	ds_write_b128 v10, v[162:165]
	s_waitcnt vmcnt(10)
	ds_write_b16 v208, v166 offset:36864
	ds_write_b16_d16_hi v208, v166 offset:37392
	ds_write_b16 v208, v167 offset:37920
	ds_write_b16_d16_hi v208, v167 offset:38448
	ds_write_b16 v208, v168 offset:38976
	ds_write_b16_d16_hi v208, v168 offset:39504
	ds_write_b16 v208, v169 offset:40032
	ds_write_b16_d16_hi v208, v169 offset:40560
	v_mad_u32_u24 v10, v141, s50, v12
	v_lshl_add_u32 v208, v141, 1, v13
	s_waitcnt vmcnt(9)
	ds_write_b128 v10, v[170:173]
	s_waitcnt vmcnt(8)
	ds_write_b16 v208, v174 offset:36864
	ds_write_b16_d16_hi v208, v174 offset:37392
	ds_write_b16 v208, v175 offset:37920
	ds_write_b16_d16_hi v208, v175 offset:38448
	ds_write_b16 v208, v176 offset:38976
	ds_write_b16_d16_hi v208, v176 offset:39504
	ds_write_b16 v208, v177 offset:40032
	ds_write_b16_d16_hi v208, v177 offset:40560
	v_mad_u32_u24 v10, v142, s50, v12
	v_lshl_add_u32 v208, v142, 1, v13
	s_waitcnt vmcnt(7)
	ds_write_b128 v10, v[178:181]
	s_waitcnt vmcnt(6)
	ds_write_b16 v208, v182 offset:36864
	ds_write_b16_d16_hi v208, v182 offset:37392
	ds_write_b16 v208, v183 offset:37920
	ds_write_b16_d16_hi v208, v183 offset:38448
	ds_write_b16 v208, v184 offset:38976
	ds_write_b16_d16_hi v208, v184 offset:39504
	ds_write_b16 v208, v185 offset:40032
	ds_write_b16_d16_hi v208, v185 offset:40560
	v_mad_u32_u24 v10, v143, s50, v12
	v_lshl_add_u32 v208, v143, 1, v13
	s_waitcnt vmcnt(5)
	ds_write_b128 v10, v[186:189]
	s_waitcnt vmcnt(4)
	ds_write_b16 v208, v190 offset:36864
	ds_write_b16_d16_hi v208, v190 offset:37392
	ds_write_b16 v208, v191 offset:37920
	ds_write_b16_d16_hi v208, v191 offset:38448
	ds_write_b16 v208, v192 offset:38976
	ds_write_b16_d16_hi v208, v192 offset:39504
	ds_write_b16 v208, v193 offset:40032
	ds_write_b16_d16_hi v208, v193 offset:40560
	v_mad_u32_u24 v10, v144, s50, v12
	v_lshl_add_u32 v208, v144, 1, v13
	s_waitcnt vmcnt(3)
	ds_write_b128 v10, v[194:197]
	s_waitcnt vmcnt(2)
	ds_write_b16 v208, v198 offset:36864
	ds_write_b16_d16_hi v208, v198 offset:37392
	ds_write_b16 v208, v199 offset:37920
	ds_write_b16_d16_hi v208, v199 offset:38448
	ds_write_b16 v208, v200 offset:38976
	ds_write_b16_d16_hi v208, v200 offset:39504
	ds_write_b16 v208, v201 offset:40032
	ds_write_b16_d16_hi v208, v201 offset:40560
	s_branch .LBB0_764
